# G23/G23C: touch epilogue sum-of-squares lines via LDS-DMA sink at K-loop entry
# speedup vs baseline: 1.0029x; 1.0029x over previous
.LBB0_1335:
	s_ashr_i32 s41, s40, 31
	s_lshl_b64 s[44:45], s[40:41], 17
	s_cmp_eq_u32 s75, 1
	s_cselect_b32 s2, s17, 0xc80000
	s_cselect_b32 s21, 0xc80000, s17
	s_cmp_eq_u32 s75, 0
	s_cselect_b32 s2, 0x3f00000, s2
	s_cselect_b32 s41, 0xc00000, s21
	s_add_u32 s2, s80, s2
	s_addc_u32 s21, s81, 0
	s_add_u32 s44, s2, s44
	s_addc_u32 s45, s21, s45
	s_ashr_i32 s21, s20, 31
	s_lshl_b64 s[46:47], s[20:21], 17
	s_add_u32 s2, s80, s41
	s_addc_u32 s21, s81, 0
	s_add_u32 s46, s2, s46
	v_mov_b32_e32 v125, 0
	s_addc_u32 s47, s21, s47
	s_andn2_b64 vcc, exec, s[24:25]
	v_mov_b32_e32 v124, v125
	v_mov_b32_e32 v123, v125
	v_mov_b32_e32 v122, v125
	v_mov_b32_e32 v129, v125
	v_mov_b32_e32 v128, v125
	v_mov_b32_e32 v127, v125
	v_mov_b32_e32 v126, v125
	v_mov_b32_e32 v121, v125
	v_mov_b32_e32 v120, v125
	v_mov_b32_e32 v119, v125
	v_mov_b32_e32 v118, v125
	v_mov_b32_e32 v117, v125
	v_mov_b32_e32 v116, v125
	v_mov_b32_e32 v115, v125
	v_mov_b32_e32 v114, v125
	v_mov_b32_e32 v113, v125
	v_mov_b32_e32 v112, v125
	v_mov_b32_e32 v111, v125
	v_mov_b32_e32 v110, v125
	v_mov_b32_e32 v109, v125
	v_mov_b32_e32 v108, v125
	v_mov_b32_e32 v107, v125
	v_mov_b32_e32 v106, v125
	v_mov_b32_e32 v105, v125
	v_mov_b32_e32 v104, v125
	v_mov_b32_e32 v103, v125
	v_mov_b32_e32 v102, v125
	v_mov_b32_e32 v101, v125
	v_mov_b32_e32 v100, v125
	v_mov_b32_e32 v99, v125
	v_mov_b32_e32 v98, v125
	v_mov_b32_e32 v65, v125
	v_mov_b32_e32 v64, v125
	v_mov_b32_e32 v63, v125
	v_mov_b32_e32 v62, v125
	v_mov_b32_e32 v61, v125
	v_mov_b32_e32 v60, v125
	v_mov_b32_e32 v59, v125
	v_mov_b32_e32 v58, v125
	v_mov_b32_e32 v57, v125
	v_mov_b32_e32 v56, v125
	v_mov_b32_e32 v55, v125
	v_mov_b32_e32 v54, v125
	v_mov_b32_e32 v53, v125
	v_mov_b32_e32 v52, v125
	v_mov_b32_e32 v51, v125
	v_mov_b32_e32 v50, v125
	v_mov_b32_e32 v49, v125
	v_mov_b32_e32 v48, v125
	v_mov_b32_e32 v47, v125
	v_mov_b32_e32 v46, v125
	v_mov_b32_e32 v45, v125
	v_mov_b32_e32 v44, v125
	v_mov_b32_e32 v43, v125
	v_mov_b32_e32 v42, v125
	v_mov_b32_e32 v41, v125
	v_mov_b32_e32 v40, v125
	v_mov_b32_e32 v39, v125
	v_mov_b32_e32 v38, v125
	v_mov_b32_e32 v37, v125
	v_mov_b32_e32 v36, v125
	v_mov_b32_e32 v35, v125
	v_mov_b32_e32 v34, v125
	v_mov_b32_e32 v97, v125
	v_mov_b32_e32 v96, v125
	v_mov_b32_e32 v95, v125
	v_mov_b32_e32 v94, v125
	v_mov_b32_e32 v93, v125
	v_mov_b32_e32 v92, v125
	v_mov_b32_e32 v91, v125
	v_mov_b32_e32 v90, v125
	v_mov_b32_e32 v89, v125
	v_mov_b32_e32 v88, v125
	v_mov_b32_e32 v87, v125
	v_mov_b32_e32 v86, v125
	v_mov_b32_e32 v85, v125
	v_mov_b32_e32 v84, v125
	v_mov_b32_e32 v83, v125
	v_mov_b32_e32 v82, v125
	v_mov_b32_e32 v81, v125
	v_mov_b32_e32 v80, v125
	v_mov_b32_e32 v79, v125
	v_mov_b32_e32 v78, v125
	v_mov_b32_e32 v77, v125
	v_mov_b32_e32 v76, v125
	v_mov_b32_e32 v75, v125
	v_mov_b32_e32 v74, v125
	v_mov_b32_e32 v73, v125
	v_mov_b32_e32 v72, v125
	v_mov_b32_e32 v71, v125
	v_mov_b32_e32 v70, v125
	v_mov_b32_e32 v69, v125
	v_mov_b32_e32 v68, v125
	v_mov_b32_e32 v67, v125
	v_mov_b32_e32 v66, v125
	v_mov_b32_e32 v33, v125
	v_mov_b32_e32 v32, v125
	v_mov_b32_e32 v31, v125
	v_mov_b32_e32 v30, v125
	v_mov_b32_e32 v29, v125
	v_mov_b32_e32 v28, v125
	v_mov_b32_e32 v27, v125
	v_mov_b32_e32 v26, v125
	v_mov_b32_e32 v25, v125
	v_mov_b32_e32 v24, v125
	v_mov_b32_e32 v23, v125
	v_mov_b32_e32 v22, v125
	v_mov_b32_e32 v21, v125
	v_mov_b32_e32 v20, v125
	v_mov_b32_e32 v19, v125
	v_mov_b32_e32 v18, v125
	v_mov_b32_e32 v17, v125
	v_mov_b32_e32 v16, v125
	v_mov_b32_e32 v15, v125
	v_mov_b32_e32 v14, v125
	v_mov_b32_e32 v13, v125
	v_mov_b32_e32 v12, v125
	v_mov_b32_e32 v11, v125
	v_mov_b32_e32 v10, v125
	v_mov_b32_e32 v9, v125
	v_mov_b32_e32 v8, v125
	v_mov_b32_e32 v7, v125
	v_mov_b32_e32 v6, v125
	v_mov_b32_e32 v5, v125
	v_mov_b32_e32 v4, v125
	v_mov_b32_e32 v3, v125
	v_mov_b32_e32 v2, v125
	s_cbranch_vccnz .LBB0_1338
	s_and_b64 s[50:51], s[42:43], exec
	s_cselect_b32 s2, s45, s9
	s_cselect_b32 s21, s44, s8
	s_cselect_b32 s41, s47, s11
	s_cselect_b32 s50, s46, s10
	s_add_u32 s8, s8, 0x80
	s_addc_u32 s9, s9, 0
	s_add_u32 s51, s10, 0x100
	v_mov_b32_e32 v2, 0
	s_addc_u32 s52, s11, 0
	s_mov_b32 s10, 0
	v_mov_b32_e32 v3, v2
	v_mov_b32_e32 v4, v2
	v_mov_b32_e32 v5, v2
	v_mov_b32_e32 v6, v2
	v_mov_b32_e32 v7, v2
	v_mov_b32_e32 v8, v2
	v_mov_b32_e32 v9, v2
	v_mov_b32_e32 v10, v2
	v_mov_b32_e32 v11, v2
	v_mov_b32_e32 v12, v2
	v_mov_b32_e32 v13, v2
	v_mov_b32_e32 v14, v2
	v_mov_b32_e32 v15, v2
	v_mov_b32_e32 v16, v2
	v_mov_b32_e32 v17, v2
	v_mov_b32_e32 v18, v2
	v_mov_b32_e32 v19, v2
	v_mov_b32_e32 v20, v2
	v_mov_b32_e32 v21, v2
	v_mov_b32_e32 v22, v2
	v_mov_b32_e32 v23, v2
	v_mov_b32_e32 v24, v2
	v_mov_b32_e32 v25, v2
	v_mov_b32_e32 v26, v2
	v_mov_b32_e32 v27, v2
	v_mov_b32_e32 v28, v2
	v_mov_b32_e32 v29, v2
	v_mov_b32_e32 v30, v2
	v_mov_b32_e32 v31, v2
	v_mov_b32_e32 v32, v2
	v_mov_b32_e32 v33, v2
	v_mov_b32_e32 v66, v2
	v_mov_b32_e32 v67, v2
	v_mov_b32_e32 v68, v2
	v_mov_b32_e32 v69, v2
	v_mov_b32_e32 v70, v2
	v_mov_b32_e32 v71, v2
	v_mov_b32_e32 v72, v2
	v_mov_b32_e32 v73, v2
	v_mov_b32_e32 v74, v2
	v_mov_b32_e32 v75, v2
	v_mov_b32_e32 v76, v2
	v_mov_b32_e32 v77, v2
	v_mov_b32_e32 v78, v2
	v_mov_b32_e32 v79, v2
	v_mov_b32_e32 v80, v2
	v_mov_b32_e32 v81, v2
	v_mov_b32_e32 v82, v2
	v_mov_b32_e32 v83, v2
	v_mov_b32_e32 v84, v2
	v_mov_b32_e32 v85, v2
	v_mov_b32_e32 v86, v2
	v_mov_b32_e32 v87, v2
	v_mov_b32_e32 v88, v2
	v_mov_b32_e32 v89, v2
	v_mov_b32_e32 v90, v2
	v_mov_b32_e32 v91, v2
	v_mov_b32_e32 v92, v2
	v_mov_b32_e32 v93, v2
	v_mov_b32_e32 v94, v2
	v_mov_b32_e32 v95, v2
	v_mov_b32_e32 v96, v2
	v_mov_b32_e32 v97, v2
	v_mov_b32_e32 v34, v2
	v_mov_b32_e32 v35, v2
	v_mov_b32_e32 v36, v2
	v_mov_b32_e32 v37, v2
	v_mov_b32_e32 v38, v2
	v_mov_b32_e32 v39, v2
	v_mov_b32_e32 v40, v2
	v_mov_b32_e32 v41, v2
	v_mov_b32_e32 v42, v2
	v_mov_b32_e32 v43, v2
	v_mov_b32_e32 v44, v2
	v_mov_b32_e32 v45, v2
	v_mov_b32_e32 v46, v2
	v_mov_b32_e32 v47, v2
	v_mov_b32_e32 v48, v2
	v_mov_b32_e32 v49, v2
	v_mov_b32_e32 v50, v2
	v_mov_b32_e32 v51, v2
	v_mov_b32_e32 v52, v2
	v_mov_b32_e32 v53, v2
	v_mov_b32_e32 v54, v2
	v_mov_b32_e32 v55, v2
	v_mov_b32_e32 v56, v2
	v_mov_b32_e32 v57, v2
	v_mov_b32_e32 v58, v2
	v_mov_b32_e32 v59, v2
	v_mov_b32_e32 v60, v2
	v_mov_b32_e32 v61, v2
	v_mov_b32_e32 v62, v2
	v_mov_b32_e32 v63, v2
	v_mov_b32_e32 v64, v2
	v_mov_b32_e32 v65, v2
	v_mov_b32_e32 v98, v2
	v_mov_b32_e32 v99, v2
	v_mov_b32_e32 v100, v2
	v_mov_b32_e32 v101, v2
	v_mov_b32_e32 v102, v2
	v_mov_b32_e32 v103, v2
	v_mov_b32_e32 v104, v2
	v_mov_b32_e32 v105, v2
	v_mov_b32_e32 v106, v2
	v_mov_b32_e32 v107, v2
	v_mov_b32_e32 v108, v2
	v_mov_b32_e32 v109, v2
	v_mov_b32_e32 v110, v2
	v_mov_b32_e32 v111, v2
	v_mov_b32_e32 v112, v2
	v_mov_b32_e32 v113, v2
	v_mov_b32_e32 v114, v2
	v_mov_b32_e32 v115, v2
	v_mov_b32_e32 v116, v2
	v_mov_b32_e32 v117, v2
	v_mov_b32_e32 v118, v2
	v_mov_b32_e32 v119, v2
	v_mov_b32_e32 v120, v2
	v_mov_b32_e32 v121, v2
	v_mov_b32_e32 v126, v2
	v_mov_b32_e32 v127, v2
	v_mov_b32_e32 v128, v2
	v_mov_b32_e32 v129, v2
	v_mov_b32_e32 v122, v2
	v_mov_b32_e32 v123, v2
	v_mov_b32_e32 v124, v2
	v_mov_b32_e32 v125, v2
	s_cmp_eq_u32 s3, 2
	s_cbranch_scc1 .Lsst3_k2
	s_cmp_eq_u32 s3, 0
	s_cselect_b32 s98, s34, s28
	s_cselect_b32 s99, s35, s29
	v_mbcnt_lo_u32_b32 v244, -1, 0
	v_mbcnt_hi_u32_b32 v244, -1, v244
	v_and_b32_e32 v245, 8, v244
	v_and_b32_e32 v244, 7, v244
	v_lshlrev_b32_e32 v245, 8, v245
	v_lshl_or_b32 v244, v244, 7, v245
	v_lshl_add_u32 v244, s62, 4, v244
	v_lshl_add_u32 v244, s48, 12, v244
	s_branch .Lsst3_go
.Lsst3_k2:
	s_mov_b32 s98, s28
	s_mov_b32 s99, s29
	v_mbcnt_lo_u32_b32 v244, -1, 0
	v_mbcnt_hi_u32_b32 v244, -1, v244
	v_and_b32_e32 v245, 4, v244
	v_and_b32_e32 v244, 3, v244
	v_lshlrev_b32_e32 v245, 9, v245
	v_lshl_or_b32 v244, v244, 7, v245
	v_lshl_add_u32 v244, s63, 4, v244
	v_lshl_add_u32 v244, s38, 12, v244
.Lsst3_go:
	v_mov_b32_e32 v245, 0
	s_mov_b32 m0, 0x22800
	v_lshl_add_u64 v[244:245], v[244:245], 0, s[98:99]
	global_load_lds_dword v[244:245], off

.LBB0_1554:
	s_ashr_i32 s31, s30, 31
	s_lshl_b64 s[38:39], s[30:31], 17
	s_cmp_eq_u32 s75, 1
	s_cselect_b32 s3, s52, 0xc80000
	s_cselect_b32 s31, 0xc80000, s52
	s_add_u32 s3, s80, s3
	s_addc_u32 s35, s81, 0
	s_add_u32 s38, s3, s38
	s_addc_u32 s39, s35, s39
	s_ashr_i32 s35, s34, 31
	s_lshl_b64 s[40:41], s[34:35], 17
	s_add_u32 s3, s80, s31
	s_addc_u32 s31, s81, 0
	s_add_u32 s40, s3, s40
	v_mov_b32_e32 v125, 0
	s_addc_u32 s41, s31, s41
	s_andn2_b64 vcc, exec, s[16:17]
	v_mov_b32_e32 v124, v125
	v_mov_b32_e32 v123, v125
	v_mov_b32_e32 v122, v125
	v_mov_b32_e32 v129, v125
	v_mov_b32_e32 v128, v125
	v_mov_b32_e32 v127, v125
	v_mov_b32_e32 v126, v125
	v_mov_b32_e32 v121, v125
	v_mov_b32_e32 v120, v125
	v_mov_b32_e32 v119, v125
	v_mov_b32_e32 v118, v125
	v_mov_b32_e32 v117, v125
	v_mov_b32_e32 v116, v125
	v_mov_b32_e32 v115, v125
	v_mov_b32_e32 v114, v125
	v_mov_b32_e32 v113, v125
	v_mov_b32_e32 v112, v125
	v_mov_b32_e32 v111, v125
	v_mov_b32_e32 v110, v125
	v_mov_b32_e32 v109, v125
	v_mov_b32_e32 v108, v125
	v_mov_b32_e32 v107, v125
	v_mov_b32_e32 v106, v125
	v_mov_b32_e32 v105, v125
	v_mov_b32_e32 v104, v125
	v_mov_b32_e32 v103, v125
	v_mov_b32_e32 v102, v125
	v_mov_b32_e32 v101, v125
	v_mov_b32_e32 v100, v125
	v_mov_b32_e32 v99, v125
	v_mov_b32_e32 v98, v125
	v_mov_b32_e32 v65, v125
	v_mov_b32_e32 v64, v125
	v_mov_b32_e32 v63, v125
	v_mov_b32_e32 v62, v125
	v_mov_b32_e32 v61, v125
	v_mov_b32_e32 v60, v125
	v_mov_b32_e32 v59, v125
	v_mov_b32_e32 v58, v125
	v_mov_b32_e32 v57, v125
	v_mov_b32_e32 v56, v125
	v_mov_b32_e32 v55, v125
	v_mov_b32_e32 v54, v125
	v_mov_b32_e32 v53, v125
	v_mov_b32_e32 v52, v125
	v_mov_b32_e32 v51, v125
	v_mov_b32_e32 v50, v125
	v_mov_b32_e32 v49, v125
	v_mov_b32_e32 v48, v125
	v_mov_b32_e32 v47, v125
	v_mov_b32_e32 v46, v125
	v_mov_b32_e32 v45, v125
	v_mov_b32_e32 v44, v125
	v_mov_b32_e32 v43, v125
	v_mov_b32_e32 v42, v125
	v_mov_b32_e32 v41, v125
	v_mov_b32_e32 v40, v125
	v_mov_b32_e32 v39, v125
	v_mov_b32_e32 v38, v125
	v_mov_b32_e32 v37, v125
	v_mov_b32_e32 v36, v125
	v_mov_b32_e32 v35, v125
	v_mov_b32_e32 v34, v125
	v_mov_b32_e32 v97, v125
	v_mov_b32_e32 v96, v125
	v_mov_b32_e32 v95, v125
	v_mov_b32_e32 v94, v125
	v_mov_b32_e32 v93, v125
	v_mov_b32_e32 v92, v125
	v_mov_b32_e32 v91, v125
	v_mov_b32_e32 v90, v125
	v_mov_b32_e32 v89, v125
	v_mov_b32_e32 v88, v125
	v_mov_b32_e32 v87, v125
	v_mov_b32_e32 v86, v125
	v_mov_b32_e32 v85, v125
	v_mov_b32_e32 v84, v125
	v_mov_b32_e32 v83, v125
	v_mov_b32_e32 v82, v125
	v_mov_b32_e32 v81, v125
	v_mov_b32_e32 v80, v125
	v_mov_b32_e32 v79, v125
	v_mov_b32_e32 v78, v125
	v_mov_b32_e32 v77, v125
	v_mov_b32_e32 v76, v125
	v_mov_b32_e32 v75, v125
	v_mov_b32_e32 v74, v125
	v_mov_b32_e32 v73, v125
	v_mov_b32_e32 v72, v125
	v_mov_b32_e32 v71, v125
	v_mov_b32_e32 v70, v125
	v_mov_b32_e32 v69, v125
	v_mov_b32_e32 v68, v125
	v_mov_b32_e32 v67, v125
	v_mov_b32_e32 v66, v125
	v_mov_b32_e32 v33, v125
	v_mov_b32_e32 v32, v125
	v_mov_b32_e32 v31, v125
	v_mov_b32_e32 v30, v125
	v_mov_b32_e32 v29, v125
	v_mov_b32_e32 v28, v125
	v_mov_b32_e32 v27, v125
	v_mov_b32_e32 v26, v125
	v_mov_b32_e32 v25, v125
	v_mov_b32_e32 v24, v125
	v_mov_b32_e32 v23, v125
	v_mov_b32_e32 v22, v125
	v_mov_b32_e32 v21, v125
	v_mov_b32_e32 v20, v125
	v_mov_b32_e32 v19, v125
	v_mov_b32_e32 v18, v125
	v_mov_b32_e32 v17, v125
	v_mov_b32_e32 v16, v125
	v_mov_b32_e32 v15, v125
	v_mov_b32_e32 v14, v125
	v_mov_b32_e32 v13, v125
	v_mov_b32_e32 v12, v125
	v_mov_b32_e32 v11, v125
	v_mov_b32_e32 v10, v125
	v_mov_b32_e32 v9, v125
	v_mov_b32_e32 v8, v125
	v_mov_b32_e32 v7, v125
	v_mov_b32_e32 v6, v125
	v_mov_b32_e32 v5, v125
	v_mov_b32_e32 v4, v125
	v_mov_b32_e32 v3, v125
	v_mov_b32_e32 v2, v125
	s_cbranch_vccnz .LBB0_1557
	s_and_b64 s[46:47], s[36:37], exec
	s_cselect_b32 s3, s39, s7
	s_cselect_b32 s31, s38, s6
	s_cselect_b32 s35, s41, s9
	s_cselect_b32 s45, s40, s8
	s_add_u32 s6, s6, 0x80
	s_addc_u32 s7, s7, 0
	s_add_u32 s46, s8, 0x100
	v_mov_b32_e32 v2, 0
	s_addc_u32 s47, s9, 0
	s_mov_b32 s8, 0
	v_mov_b32_e32 v3, v2
	v_mov_b32_e32 v4, v2
	v_mov_b32_e32 v5, v2
	v_mov_b32_e32 v6, v2
	v_mov_b32_e32 v7, v2
	v_mov_b32_e32 v8, v2
	v_mov_b32_e32 v9, v2
	v_mov_b32_e32 v10, v2
	v_mov_b32_e32 v11, v2
	v_mov_b32_e32 v12, v2
	v_mov_b32_e32 v13, v2
	v_mov_b32_e32 v14, v2
	v_mov_b32_e32 v15, v2
	v_mov_b32_e32 v16, v2
	v_mov_b32_e32 v17, v2
	v_mov_b32_e32 v18, v2
	v_mov_b32_e32 v19, v2
	v_mov_b32_e32 v20, v2
	v_mov_b32_e32 v21, v2
	v_mov_b32_e32 v22, v2
	v_mov_b32_e32 v23, v2
	v_mov_b32_e32 v24, v2
	v_mov_b32_e32 v25, v2
	v_mov_b32_e32 v26, v2
	v_mov_b32_e32 v27, v2
	v_mov_b32_e32 v28, v2
	v_mov_b32_e32 v29, v2
	v_mov_b32_e32 v30, v2
	v_mov_b32_e32 v31, v2
	v_mov_b32_e32 v32, v2
	v_mov_b32_e32 v33, v2
	v_mov_b32_e32 v66, v2
	v_mov_b32_e32 v67, v2
	v_mov_b32_e32 v68, v2
	v_mov_b32_e32 v69, v2
	v_mov_b32_e32 v70, v2
	v_mov_b32_e32 v71, v2
	v_mov_b32_e32 v72, v2
	v_mov_b32_e32 v73, v2
	v_mov_b32_e32 v74, v2
	v_mov_b32_e32 v75, v2
	v_mov_b32_e32 v76, v2
	v_mov_b32_e32 v77, v2
	v_mov_b32_e32 v78, v2
	v_mov_b32_e32 v79, v2
	v_mov_b32_e32 v80, v2
	v_mov_b32_e32 v81, v2
	v_mov_b32_e32 v82, v2
	v_mov_b32_e32 v83, v2
	v_mov_b32_e32 v84, v2
	v_mov_b32_e32 v85, v2
	v_mov_b32_e32 v86, v2
	v_mov_b32_e32 v87, v2
	v_mov_b32_e32 v88, v2
	v_mov_b32_e32 v89, v2
	v_mov_b32_e32 v90, v2
	v_mov_b32_e32 v91, v2
	v_mov_b32_e32 v92, v2
	v_mov_b32_e32 v93, v2
	v_mov_b32_e32 v94, v2
	v_mov_b32_e32 v95, v2
	v_mov_b32_e32 v96, v2
	v_mov_b32_e32 v97, v2
	v_mov_b32_e32 v34, v2
	v_mov_b32_e32 v35, v2
	v_mov_b32_e32 v36, v2
	v_mov_b32_e32 v37, v2
	v_mov_b32_e32 v38, v2
	v_mov_b32_e32 v39, v2
	v_mov_b32_e32 v40, v2
	v_mov_b32_e32 v41, v2
	v_mov_b32_e32 v42, v2
	v_mov_b32_e32 v43, v2
	v_mov_b32_e32 v44, v2
	v_mov_b32_e32 v45, v2
	v_mov_b32_e32 v46, v2
	v_mov_b32_e32 v47, v2
	v_mov_b32_e32 v48, v2
	v_mov_b32_e32 v49, v2
	v_mov_b32_e32 v50, v2
	v_mov_b32_e32 v51, v2
	v_mov_b32_e32 v52, v2
	v_mov_b32_e32 v53, v2
	v_mov_b32_e32 v54, v2
	v_mov_b32_e32 v55, v2
	v_mov_b32_e32 v56, v2
	v_mov_b32_e32 v57, v2
	v_mov_b32_e32 v58, v2
	v_mov_b32_e32 v59, v2
	v_mov_b32_e32 v60, v2
	v_mov_b32_e32 v61, v2
	v_mov_b32_e32 v62, v2
	v_mov_b32_e32 v63, v2
	v_mov_b32_e32 v64, v2
	v_mov_b32_e32 v65, v2
	v_mov_b32_e32 v98, v2
	v_mov_b32_e32 v99, v2
	v_mov_b32_e32 v100, v2
	v_mov_b32_e32 v101, v2
	v_mov_b32_e32 v102, v2
	v_mov_b32_e32 v103, v2
	v_mov_b32_e32 v104, v2
	v_mov_b32_e32 v105, v2
	v_mov_b32_e32 v106, v2
	v_mov_b32_e32 v107, v2
	v_mov_b32_e32 v108, v2
	v_mov_b32_e32 v109, v2
	v_mov_b32_e32 v110, v2
	v_mov_b32_e32 v111, v2
	v_mov_b32_e32 v112, v2
	v_mov_b32_e32 v113, v2
	v_mov_b32_e32 v114, v2
	v_mov_b32_e32 v115, v2
	v_mov_b32_e32 v116, v2
	v_mov_b32_e32 v117, v2
	v_mov_b32_e32 v118, v2
	v_mov_b32_e32 v119, v2
	v_mov_b32_e32 v120, v2
	v_mov_b32_e32 v121, v2
	v_mov_b32_e32 v126, v2
	v_mov_b32_e32 v127, v2
	v_mov_b32_e32 v128, v2
	v_mov_b32_e32 v129, v2
	v_mov_b32_e32 v122, v2
	v_mov_b32_e32 v123, v2
	v_mov_b32_e32 v124, v2
	v_mov_b32_e32 v125, v2
	s_cmp_eq_u32 s44, 2
	s_cbranch_scc1 .Lsst4_k2
	s_cmp_eq_u32 s44, 0
	s_cselect_b32 s98, s20, s20
	s_cselect_b32 s99, s21, s21
	v_mbcnt_lo_u32_b32 v244, -1, 0
	v_mbcnt_hi_u32_b32 v244, -1, v244
	v_and_b32_e32 v245, 8, v244
	v_and_b32_e32 v244, 7, v244
	v_lshlrev_b32_e32 v245, 8, v245
	v_lshl_or_b32 v244, v244, 7, v245
	v_lshl_add_u32 v244, s62, 4, v244
	v_lshl_add_u32 v244, s42, 12, v244
	s_branch .Lsst4_go
.Lsst4_k2:
	s_mov_b32 s98, s20
	s_mov_b32 s99, s21
	v_mbcnt_lo_u32_b32 v244, -1, 0
	v_mbcnt_hi_u32_b32 v244, -1, v244
	v_and_b32_e32 v245, 4, v244
	v_and_b32_e32 v244, 3, v244
	v_lshlrev_b32_e32 v245, 9, v245
	v_lshl_or_b32 v244, v244, 7, v245
	v_lshl_add_u32 v244, s63, 4, v244
	v_lshl_add_u32 v244, s28, 12, v244
